# byte-phase pinning: heads of the hot steady loops (three GEMM K-loops, two attention tile loops) aligned to 64 bytes; on top of v57
# speedup vs baseline: 1.0109x; 1.0039x over previous
.LBB0_616:
	v_lshlrev_b32_e32 v0, 1, v189
	s_add_i32 s96, s81, 4
	v_and_b32_e32 v0, 32, v0
	s_movk_i32 s0, 0xc0
	v_and_or_b32 v0, v42, s0, v0
	v_and_b32_e32 v42, 0x100, v43
	s_cmp_lg_u32 0, -1
	v_or3_b32 v0, v0, v42, v40
	s_cselect_b32 s0, 0, 0
	v_add_u32_e32 v195, s0, v0
	v_max_f32_e32 v0, v19, v19
	v_max_f32_e32 v42, v18, v18
	v_max_f32_e32 v0, v42, v0
	v_max3_f32 v0, v0, v20, v21
	v_max3_f32 v0, v0, v22, v23
	v_max3_f32 v0, v0, v24, v25
	v_max3_f32 v0, v0, v26, v27
	v_max3_f32 v0, v0, v28, v29
	v_max3_f32 v0, v0, v30, v31
	v_max3_f32 v0, v0, v32, v33
	v_max3_f32 v0, v0, v2, v3
	v_max3_f32 v0, v0, v4, v5
	v_max3_f32 v0, v0, v6, v7
	v_max3_f32 v0, v0, v8, v9
	v_max3_f32 v0, v0, v10, v11
	v_max3_f32 v0, v0, v12, v13
	v_max3_f32 v0, v0, v14, v15
	v_max3_f32 v0, v0, v16, v17
	v_mov_b32_e32 v42, v0
	s_nop 1
	v_permlane32_swap_b32_e32 v0, v42
	v_max_f32_e32 v42, v42, v42
	v_max_f32_e32 v0, v0, v0
	v_max_f32_e32 v0, v0, v42
	v_add_f32_e32 v42, 0x7149f2ca, v0
	v_mul_f32_e32 v42, 0x3d93cd3a, v42
	s_mov_b32 s0, 0x41000000
	v_max_f32_e32 v0, 0xf149f2ca, v0
	v_cmp_ge_f32_e32 vcc, s0, v42
	v_sub_f32_e32 v42, 0xf149f2ca, v0
	v_mul_f32_e32 v42, 0x3dd53b94, v42
	v_exp_f32_e32 v42, v42
	s_cmp_eq_u64 vcc, exec
	s_cselect_b64 vcc, -1, 0
	v_cndmask_b32_e32 v197, v0, v238, vcc
	v_readlane_b32 s5, v253, 1
	v_mul_f32_e32 v0, 0xbdd53b94, v197
	v_cndmask_b32_e64 v206, v42, 1.0, vcc
	v_lshl_add_u32 v194, v192, 2, s5
	v_lshl_add_u32 v193, v34, 2, s5
	v_readlane_b32 s5, v252, 7
	v_fmamk_f32 v18, v18, 0x3dd53b94, v0
	v_fmamk_f32 v19, v19, 0x3dd53b94, v0
	v_fmamk_f32 v20, v20, 0x3dd53b94, v0
	v_fmamk_f32 v21, v21, 0x3dd53b94, v0
	v_fmamk_f32 v22, v22, 0x3dd53b94, v0
	v_fmamk_f32 v23, v23, 0x3dd53b94, v0
	v_fmamk_f32 v24, v24, 0x3dd53b94, v0
	v_fmamk_f32 v25, v25, 0x3dd53b94, v0
	v_fmamk_f32 v26, v26, 0x3dd53b94, v0
	v_fmamk_f32 v27, v27, 0x3dd53b94, v0
	v_fmamk_f32 v28, v28, 0x3dd53b94, v0
	v_fmamk_f32 v29, v29, 0x3dd53b94, v0
	v_fmamk_f32 v30, v30, 0x3dd53b94, v0
	v_fmamk_f32 v31, v31, 0x3dd53b94, v0
	v_fmamk_f32 v32, v32, 0x3dd53b94, v0
	v_mov_b32_e32 v42, v0
	v_pk_fma_f32 v[142:143], v[16:17], s[84:85], v[0:1] op_sel_hi:[1,0,0]
	v_pk_fma_f32 v[140:141], v[14:15], s[84:85], v[0:1] op_sel_hi:[1,0,0]
	v_pk_fma_f32 v[138:139], v[12:13], s[84:85], v[0:1] op_sel_hi:[1,0,0]
	v_pk_fma_f32 v[136:137], v[10:11], s[84:85], v[0:1] op_sel_hi:[1,0,0]
	v_pk_fma_f32 v[134:135], v[8:9], s[84:85], v[0:1] op_sel_hi:[1,0,0]
	v_pk_fma_f32 v[132:133], v[6:7], s[84:85], v[0:1] op_sel_hi:[1,0,0]
	v_pk_fma_f32 v[130:131], v[4:5], s[84:85], v[0:1] op_sel_hi:[1,0,0]
	v_pk_fma_f32 v[128:129], v[2:3], s[84:85], v[0:1] op_sel_hi:[1,0,0]
	v_add3_u32 v0, s5, v41, v38
	v_fmac_f32_e32 v42, 0x3dd53b94, v33
	v_lshl_or_b32 v0, v0, 11, s72
	v_readlane_b32 s5, v253, 13
	v_exp_f32_e32 v112, v18
	v_exp_f32_e32 v113, v19
	v_exp_f32_e32 v114, v20
	v_exp_f32_e32 v115, v21
	v_exp_f32_e32 v116, v22
	v_exp_f32_e32 v117, v23
	v_exp_f32_e32 v118, v24
	v_exp_f32_e32 v119, v25
	v_exp_f32_e32 v120, v26
	v_exp_f32_e32 v121, v27
	v_exp_f32_e32 v122, v28
	v_exp_f32_e32 v123, v29
	v_exp_f32_e32 v124, v30
	v_exp_f32_e32 v125, v31
	v_exp_f32_e32 v126, v32
	v_exp_f32_e32 v127, v42
	v_add3_u32 v0, v0, v39, v40
	s_add_i32 s5, s5, s92
	s_waitcnt vmcnt(2)
	v_lshl_add_u32 v207, v0, 1, v239
	v_add_u32_e32 v0, s5, v192
	v_mov_b32_e32 v14, v1
	v_mov_b32_e32 v15, v1
	s_lshr_b32 s93, s82, 6
	v_sub_u32_e32 v208, v0, v34
	v_add_u32_e32 v209, s87, v37
	v_add_u32_e32 v210, s87, v36
	v_add_u32_e32 v211, s87, v35
	v_mov_b32_e32 v0, v1
	v_mov_b32_e32 v2, v1
	v_mov_b32_e32 v3, v1
	v_mov_b32_e32 v4, v1
	v_mov_b32_e32 v5, v1
	v_mov_b32_e32 v6, v1
	v_mov_b32_e32 v7, v1
	v_mov_b32_e32 v8, v1
	v_mov_b32_e32 v9, v1
	v_mov_b32_e32 v10, v1
	v_mov_b32_e32 v11, v1
	v_mov_b32_e32 v12, v1
	v_mov_b32_e32 v13, v1
	v_mov_b64_e32 v[78:79], v[14:15]
	v_mov_b64_e32 v[62:63], v[14:15]
	v_mov_b64_e32 v[46:47], v[14:15]
	v_mov_b64_e32 v[30:31], v[14:15]
	v_mov_b64_e32 v[94:95], v[14:15]
	s_mov_b32 s75, 1
	s_mov_b32 s4, 0
	s_add_i32 s0, s93, 1
	v_cmp_gt_u32_e64 s[2:3], 32, v189
	s_mov_b32 s1, 2
	v_mov_b32_e32 v199, 0
	s_movk_i32 s72, 0x7f
	s_mov_b32 s79, 3
	v_mov_b64_e32 v[76:77], v[12:13]
	v_mov_b64_e32 v[74:75], v[10:11]
	v_mov_b64_e32 v[72:73], v[8:9]
	v_mov_b64_e32 v[70:71], v[6:7]
	v_mov_b64_e32 v[68:69], v[4:5]
	v_mov_b64_e32 v[66:67], v[2:3]
	v_mov_b64_e32 v[64:65], v[0:1]
	v_mov_b64_e32 v[60:61], v[12:13]
	v_mov_b64_e32 v[58:59], v[10:11]
	v_mov_b64_e32 v[56:57], v[8:9]
	v_mov_b64_e32 v[54:55], v[6:7]
	v_mov_b64_e32 v[52:53], v[4:5]
	v_mov_b64_e32 v[50:51], v[2:3]
	v_mov_b64_e32 v[48:49], v[0:1]
	v_mov_b64_e32 v[44:45], v[12:13]
	v_mov_b64_e32 v[42:43], v[10:11]
	v_mov_b64_e32 v[40:41], v[8:9]
	v_mov_b64_e32 v[38:39], v[6:7]
	v_mov_b64_e32 v[36:37], v[4:5]
	v_mov_b64_e32 v[34:35], v[2:3]
	v_mov_b64_e32 v[32:33], v[0:1]
	v_mov_b64_e32 v[28:29], v[12:13]
	v_mov_b64_e32 v[26:27], v[10:11]
	v_mov_b64_e32 v[24:25], v[8:9]
	v_mov_b64_e32 v[22:23], v[6:7]
	v_mov_b64_e32 v[20:21], v[4:5]
	v_mov_b64_e32 v[18:19], v[2:3]
	v_mov_b64_e32 v[16:17], v[0:1]
	v_mov_b64_e32 v[92:93], v[12:13]
	v_mov_b64_e32 v[90:91], v[10:11]
	v_mov_b64_e32 v[88:89], v[8:9]
	v_mov_b64_e32 v[86:87], v[6:7]
	v_mov_b64_e32 v[84:85], v[4:5]
	v_mov_b64_e32 v[82:83], v[2:3]
	v_mov_b64_e32 v[80:81], v[0:1]
	s_barrier
	.p2align	6

.LBB0_803:
	v_lshlrev_b32_e32 v40, 1, v148
	s_add_i32 s80, s81, 4
	v_and_b32_e32 v40, 32, v40
	s_movk_i32 s0, 0xc0
	v_and_or_b32 v40, v34, s0, v40
	v_and_b32_e32 v38, 0x100, v38
	s_cmp_lg_u32 0, -1
	v_or3_b32 v38, v40, v38, v36
	s_cselect_b32 s0, 0, 0
	v_add_u32_e32 v153, s0, v38
	v_max_f32_e32 v38, v19, v19
	v_max_f32_e32 v40, v18, v18
	v_max_f32_e32 v38, v40, v38
	v_max3_f32 v38, v38, v20, v21
	v_max3_f32 v38, v38, v22, v23
	v_max3_f32 v38, v38, v24, v25
	v_max3_f32 v38, v38, v26, v27
	v_max3_f32 v38, v38, v28, v29
	v_max3_f32 v38, v38, v30, v31
	v_max3_f32 v38, v38, v32, v33
	v_max3_f32 v38, v38, v2, v3
	v_max3_f32 v38, v38, v4, v5
	v_max3_f32 v38, v38, v6, v7
	v_max3_f32 v38, v38, v8, v9
	v_max3_f32 v38, v38, v10, v11
	v_max3_f32 v38, v38, v12, v13
	v_max3_f32 v38, v38, v14, v15
	v_max3_f32 v38, v38, v16, v17
	v_mov_b32_e32 v40, v38
	s_nop 1
	v_permlane32_swap_b32_e32 v38, v40
	v_readlane_b32 s1, v253, 1
	v_max_f32_e32 v40, v40, v40
	v_max_f32_e32 v38, v38, v38
	v_lshl_add_u32 v152, v150, 2, s1
	v_lshl_add_u32 v151, v39, 2, s1
	v_readlane_b32 s1, v252, 11
	v_max_f32_e32 v38, v38, v40
	v_add_f32_e32 v40, 0x7149f2ca, v38
	v_add3_u32 v0, s1, v37, v0
	v_lshl_or_b32 v0, v0, 11, s72
	v_mul_f32_e32 v40, 0x3d93cd3a, v40
	s_mov_b32 s0, 0x41000000
	v_add3_u32 v0, v0, v35, v36
	v_readlane_b32 s1, v253, 55
	v_cmp_ge_f32_e32 vcc, s0, v40
	v_lshl_add_u32 v190, v0, 1, v239
	v_add_u32_e32 v0, s1, v34
	s_mov_b32 s5, 0x51eb851f
	s_cmp_eq_u64 vcc, exec
	v_mul_hi_u32 v0, v0, s5
	v_readlane_b32 s1, v253, 13
	s_cselect_b64 vcc, -1, 0
	v_bfe_u32 v0, v0, 7, 6
	s_add_i32 s1, s1, s92
	v_max_f32_e32 v38, 0xf149f2ca, v38
	v_add_u32_e32 v191, s87, v0
	v_add_u32_e32 v0, s1, v150
	v_readlane_b32 s1, v253, 57
	v_sub_f32_e32 v40, 0xf149f2ca, v38
	v_sub_u32_e32 v192, v0, v39
	v_add_u32_e32 v0, s1, v34
	v_mul_f32_e32 v40, 0x3dd53b94, v40
	v_mul_hi_u32 v0, v0, s5
	v_exp_f32_e32 v40, v40
	v_bfe_u32 v0, v0, 7, 6
	v_readlane_b32 s1, v253, 59
	v_add_u32_e32 v193, s87, v0
	v_cndmask_b32_e32 v154, v38, v238, vcc
	v_add_u32_e32 v0, s1, v34
	v_mul_hi_u32 v0, v0, s5
	v_mul_f32_e32 v38, 0xbdd53b94, v154
	v_bfe_u32 v0, v0, 7, 6
	v_readlane_b32 s1, v252, 17
	v_cndmask_b32_e64 v196, v40, 1.0, vcc
	v_mov_b32_e32 v40, v38
	v_add_u32_e32 v194, s87, v0
	v_add_u32_e32 v0, s1, v34
	v_fmamk_f32 v18, v18, 0x3dd53b94, v38
	v_fmamk_f32 v19, v19, 0x3dd53b94, v38
	v_fmamk_f32 v20, v20, 0x3dd53b94, v38
	v_fmamk_f32 v21, v21, 0x3dd53b94, v38
	v_fmamk_f32 v22, v22, 0x3dd53b94, v38
	v_fmamk_f32 v23, v23, 0x3dd53b94, v38
	v_fmamk_f32 v24, v24, 0x3dd53b94, v38
	v_fmamk_f32 v25, v25, 0x3dd53b94, v38
	v_fmamk_f32 v26, v26, 0x3dd53b94, v38
	v_fmamk_f32 v27, v27, 0x3dd53b94, v38
	v_fmamk_f32 v28, v28, 0x3dd53b94, v38
	v_fmamk_f32 v29, v29, 0x3dd53b94, v38
	v_fmamk_f32 v30, v30, 0x3dd53b94, v38
	v_fmamk_f32 v31, v31, 0x3dd53b94, v38
	v_fmamk_f32 v32, v32, 0x3dd53b94, v38
	v_fmac_f32_e32 v40, 0x3dd53b94, v33
	v_mul_hi_u32 v0, v0, s5
	v_pk_fma_f32 v[100:101], v[14:15], s[84:85], v[38:39] op_sel_hi:[1,0,0]
	v_exp_f32_e32 v205, v18
	v_exp_f32_e32 v208, v19
	v_exp_f32_e32 v206, v20
	v_exp_f32_e32 v210, v21
	v_exp_f32_e32 v207, v22
	v_exp_f32_e32 v211, v23
	v_exp_f32_e32 v209, v24
	v_exp_f32_e32 v212, v25
	v_exp_f32_e32 v197, v26
	v_exp_f32_e32 v200, v27
	v_exp_f32_e32 v198, v28
	v_exp_f32_e32 v202, v29
	v_exp_f32_e32 v199, v30
	v_exp_f32_e32 v203, v31
	v_exp_f32_e32 v201, v32
	v_exp_f32_e32 v204, v40
	v_lshrrev_b32_e32 v0, 7, v0
	v_mov_b32_e32 v14, v1
	v_mov_b32_e32 v15, v1
	v_pk_fma_f32 v[98:99], v[16:17], s[84:85], v[38:39] op_sel_hi:[1,0,0]
	v_pk_fma_f32 v[102:103], v[12:13], s[84:85], v[38:39] op_sel_hi:[1,0,0]
	v_pk_fma_f32 v[104:105], v[10:11], s[84:85], v[38:39] op_sel_hi:[1,0,0]
	v_pk_fma_f32 v[106:107], v[8:9], s[84:85], v[38:39] op_sel_hi:[1,0,0]
	v_pk_fma_f32 v[108:109], v[6:7], s[84:85], v[38:39] op_sel_hi:[1,0,0]
	v_pk_fma_f32 v[110:111], v[4:5], s[84:85], v[38:39] op_sel_hi:[1,0,0]
	v_pk_fma_f32 v[112:113], v[2:3], s[84:85], v[38:39] op_sel_hi:[1,0,0]
	s_waitcnt vmcnt(2)
	v_add_u32_e32 v195, s87, v0
	v_mov_b32_e32 v0, v1
	v_mov_b32_e32 v2, v1
	v_mov_b32_e32 v3, v1
	v_mov_b32_e32 v4, v1
	v_mov_b32_e32 v5, v1
	v_mov_b32_e32 v6, v1
	v_mov_b32_e32 v7, v1
	v_mov_b32_e32 v8, v1
	v_mov_b32_e32 v9, v1
	v_mov_b32_e32 v10, v1
	v_mov_b32_e32 v11, v1
	v_mov_b32_e32 v12, v1
	v_mov_b32_e32 v13, v1
	v_mov_b64_e32 v[64:65], v[14:15]
	v_mov_b64_e32 v[48:49], v[14:15]
	v_mov_b64_e32 v[32:33], v[14:15]
	s_lshr_b32 s96, s82, 6
	v_mov_b64_e32 v[62:63], v[12:13]
	v_mov_b64_e32 v[60:61], v[10:11]
	v_mov_b64_e32 v[58:59], v[8:9]
	v_mov_b64_e32 v[56:57], v[6:7]
	v_mov_b64_e32 v[54:55], v[4:5]
	v_mov_b64_e32 v[52:53], v[2:3]
	v_mov_b64_e32 v[50:51], v[0:1]
	v_mov_b64_e32 v[46:47], v[12:13]
	v_mov_b64_e32 v[44:45], v[10:11]
	v_mov_b64_e32 v[42:43], v[8:9]
	v_mov_b64_e32 v[40:41], v[6:7]
	v_mov_b64_e32 v[38:39], v[4:5]
	v_mov_b64_e32 v[36:37], v[2:3]
	v_mov_b64_e32 v[34:35], v[0:1]
	v_mov_b64_e32 v[30:31], v[12:13]
	v_mov_b64_e32 v[28:29], v[10:11]
	v_mov_b64_e32 v[26:27], v[8:9]
	v_mov_b64_e32 v[24:25], v[6:7]
	v_mov_b64_e32 v[22:23], v[4:5]
	v_mov_b64_e32 v[20:21], v[2:3]
	v_mov_b64_e32 v[18:19], v[0:1]
	v_mov_b64_e32 v[16:17], v[14:15]
	s_mov_b32 s97, 1
	s_mov_b32 s4, 0
	s_add_i32 s79, s96, 1
	v_cmp_gt_u32_e64 s[2:3], 32, v148
	s_mov_b32 s0, 2
	v_mov_b32_e32 v157, 0
	s_movk_i32 s1, 0x7f
	s_mov_b32 s72, 3
	v_mov_b64_e32 v[14:15], v[12:13]
	v_mov_b64_e32 v[12:13], v[10:11]
	v_mov_b64_e32 v[10:11], v[8:9]
	v_mov_b64_e32 v[8:9], v[6:7]
	v_mov_b64_e32 v[6:7], v[4:5]
	v_mov_b64_e32 v[4:5], v[2:3]
	v_mov_b64_e32 v[2:3], v[0:1]
	v_mov_b32_e32 v166, 0
	v_mov_b32_e32 v169, 0
	v_mov_b32_e32 v168, 0
	v_mov_b32_e32 v173, 0
	v_mov_b32_e32 v172, 0
	v_mov_b32_e32 v177, 0
	v_mov_b32_e32 v176, 0
	v_mov_b32_e32 v188, 0
	v_mov_b32_e32 v167, 0
	v_mov_b32_e32 v171, 0
	v_mov_b32_e32 v170, 0
	v_mov_b32_e32 v175, 0
	v_mov_b32_e32 v174, 0
	v_mov_b32_e32 v179, 0
	v_mov_b32_e32 v178, 0
	v_mov_b32_e32 v189, 0
	s_barrier
	.p2align	6

.LBB0_1051:
	s_add_u32 s8, s34, 0x180
	s_waitcnt lgkmcnt(0)
	s_addc_u32 s9, s35, 0
	s_add_u32 s36, s30, 0x180
	s_addc_u32 s37, s31, 0
	s_barrier
	s_setprio 1
	s_waitcnt lgkmcnt(7)
	v_mfma_f32_16x16x32_bf16 v[130:133], v[18:21], v[122:125], 0
	s_waitcnt lgkmcnt(6)
	v_mfma_f32_16x16x32_bf16 v[148:151], v[22:25], v[126:129], v[130:133]
	v_mfma_f32_16x16x32_bf16 v[130:133], v[26:29], v[122:125], 0
	v_mfma_f32_16x16x32_bf16 v[152:155], v[30:33], v[126:129], v[130:133]
	s_waitcnt lgkmcnt(5)
	v_mfma_f32_16x16x32_bf16 v[130:133], v[18:21], v[114:117], 0
	s_waitcnt lgkmcnt(4)
	v_mfma_f32_16x16x32_bf16 v[156:159], v[22:25], v[118:121], v[130:133]
	v_mfma_f32_16x16x32_bf16 v[130:133], v[26:29], v[114:117], 0
	v_mfma_f32_16x16x32_bf16 v[160:163], v[30:33], v[118:121], v[130:133]
	s_waitcnt lgkmcnt(3)
	v_mfma_f32_16x16x32_bf16 v[130:133], v[18:21], v[106:109], 0
	s_waitcnt lgkmcnt(1)
	v_mfma_f32_16x16x32_bf16 v[18:21], v[18:21], v[98:101], 0
	v_mfma_f32_16x16x32_bf16 v[164:167], v[22:25], v[110:113], v[130:133]
	s_waitcnt lgkmcnt(0)
	v_mfma_f32_16x16x32_bf16 v[18:21], v[22:25], v[102:105], v[18:21]
	v_mfma_f32_16x16x32_bf16 v[22:25], v[26:29], v[98:101], 0
	v_mfma_f32_16x16x32_bf16 v[130:133], v[26:29], v[106:109], 0
	v_mfma_f32_16x16x32_bf16 v[22:25], v[30:33], v[102:105], v[22:25]
	v_mfma_f32_16x16x32_bf16 v[168:171], v[30:33], v[110:113], v[130:133]
	s_setprio 0
	s_setprio 1
	v_mfma_f32_16x16x32_bf16 v[30:33], v[10:13], v[122:125], 0
	v_mfma_f32_16x16x32_bf16 v[172:175], v[14:17], v[126:129], v[30:33]
	v_mfma_f32_16x16x32_bf16 v[30:33], v[2:5], v[114:117], 0
	v_mfma_f32_16x16x32_bf16 v[176:179], v[6:9], v[118:121], v[30:33]
	v_mfma_f32_16x16x32_bf16 v[30:33], v[10:13], v[114:117], 0
	v_mfma_f32_16x16x32_bf16 v[26:29], v[2:5], v[122:125], 0
	v_mfma_f32_16x16x32_bf16 v[182:185], v[14:17], v[118:121], v[30:33]
	v_mfma_f32_16x16x32_bf16 v[30:33], v[2:5], v[106:109], 0
	v_mfma_f32_16x16x32_bf16 v[2:5], v[2:5], v[98:101], 0
	v_mfma_f32_16x16x32_bf16 v[26:29], v[6:9], v[126:129], v[26:29]
	v_mfma_f32_16x16x32_bf16 v[186:189], v[6:9], v[110:113], v[30:33]
	v_mfma_f32_16x16x32_bf16 v[30:33], v[10:13], v[106:109], 0
	v_mfma_f32_16x16x32_bf16 v[2:5], v[6:9], v[102:105], v[2:5]
	v_mfma_f32_16x16x32_bf16 v[6:9], v[10:13], v[98:101], 0
	v_mfma_f32_16x16x32_bf16 v[106:109], v[14:17], v[110:113], v[30:33]
	v_mfma_f32_16x16x32_bf16 v[100:103], v[14:17], v[102:105], v[6:9]
	s_setprio 0
	s_barrier
	v_add_u32_e32 v98, 0x18000, v243
	v_add_u32_e32 v99, 0x1c000, v243
	s_nop 1
	ds_read_b128 v[6:9], v98
	ds_read_b128 v[10:13], v98 offset:1024
	ds_read_b128 v[14:17], v98 offset:2048
	ds_read_b128 v[30:33], v98 offset:3072
	ds_read_b128 v[110:113], v99
	ds_read_b128 v[190:193], v99 offset:1024
	ds_read_b128 v[194:197], v99 offset:2048
	ds_read_b128 v[198:201], v99 offset:3072
	ds_read_b128 v[202:205], v244 offset:32768
	ds_read_b128 v[206:209], v244 offset:33792
	ds_read_b128 v[210:213], v244 offset:34816
	ds_read_b128 v[214:217], v244 offset:35840
	ds_read_b128 v[218:221], v244 offset:36864
	ds_read_b128 v[222:225], v244 offset:37888
	ds_read_b128 v[226:229], v244 offset:38912
	ds_read_b128 v[230:233], v244 offset:39936
	s_add_u32 s66, s34, 0x80100
	s_addc_u32 s67, s35, 0
	s_mov_b32 m0, s53
	s_nop 0
	global_load_lds_dwordx4 v0, s[66:67]
	s_nop 0
	s_mov_b32 m0, s54
	s_nop 0
	global_load_lds_dwordx4 v241, s[66:67]
	s_waitcnt vmcnt(8)
	s_waitcnt lgkmcnt(0)
	s_barrier
	s_setprio 1
	s_waitcnt lgkmcnt(7)
	v_mfma_f32_16x16x32_bf16 v[34:37], v[6:9], v[202:205], v[34:37]
	s_waitcnt lgkmcnt(6)
	v_mfma_f32_16x16x32_bf16 v[142:145], v[10:13], v[206:209], v[34:37]
	v_mfma_f32_16x16x32_bf16 v[34:37], v[14:17], v[202:205], v[38:41]
	v_mfma_f32_16x16x32_bf16 v[138:141], v[30:33], v[206:209], v[34:37]
	s_waitcnt lgkmcnt(5)
	v_mfma_f32_16x16x32_bf16 v[34:37], v[6:9], v[210:213], v[42:45]
	s_waitcnt lgkmcnt(4)
	v_mfma_f32_16x16x32_bf16 v[134:137], v[10:13], v[214:217], v[34:37]
	v_mfma_f32_16x16x32_bf16 v[34:37], v[14:17], v[210:213], v[46:49]
	v_mfma_f32_16x16x32_bf16 v[130:133], v[30:33], v[214:217], v[34:37]
	s_waitcnt lgkmcnt(3)
	v_mfma_f32_16x16x32_bf16 v[34:37], v[6:9], v[218:221], v[50:53]
	s_waitcnt lgkmcnt(2)
	v_mfma_f32_16x16x32_bf16 v[126:129], v[10:13], v[222:225], v[34:37]
	v_mfma_f32_16x16x32_bf16 v[34:37], v[14:17], v[218:221], v[54:57]
	v_mfma_f32_16x16x32_bf16 v[122:125], v[30:33], v[222:225], v[34:37]
	s_waitcnt lgkmcnt(1)
	v_mfma_f32_16x16x32_bf16 v[34:37], v[6:9], v[226:229], v[58:61]
	s_waitcnt lgkmcnt(0)
	v_mfma_f32_16x16x32_bf16 v[118:121], v[10:13], v[230:233], v[34:37]
	v_mfma_f32_16x16x32_bf16 v[34:37], v[14:17], v[226:229], v[62:65]
	v_mfma_f32_16x16x32_bf16 v[114:117], v[30:33], v[230:233], v[34:37]
	s_setprio 0
	s_setprio 1
	v_mfma_f32_16x16x32_bf16 v[34:37], v[110:113], v[202:205], v[66:69]
	v_mfma_f32_16x16x32_bf16 v[62:65], v[190:193], v[206:209], v[34:37]
	v_mfma_f32_16x16x32_bf16 v[34:37], v[194:197], v[202:205], v[70:73]
	v_mfma_f32_16x16x32_bf16 v[58:61], v[198:201], v[206:209], v[34:37]
	v_mfma_f32_16x16x32_bf16 v[34:37], v[110:113], v[210:213], v[74:77]
	v_mfma_f32_16x16x32_bf16 v[54:57], v[190:193], v[214:217], v[34:37]
	v_mfma_f32_16x16x32_bf16 v[34:37], v[194:197], v[210:213], v[78:81]
	v_mfma_f32_16x16x32_bf16 v[50:53], v[198:201], v[214:217], v[34:37]
	v_mfma_f32_16x16x32_bf16 v[34:37], v[110:113], v[218:221], v[82:85]
	v_mfma_f32_16x16x32_bf16 v[46:49], v[190:193], v[222:225], v[34:37]
	v_mfma_f32_16x16x32_bf16 v[34:37], v[194:197], v[218:221], v[86:89]
	v_mfma_f32_16x16x32_bf16 v[42:45], v[198:201], v[222:225], v[34:37]
	v_mfma_f32_16x16x32_bf16 v[34:37], v[110:113], v[226:229], v[90:93]
	v_mfma_f32_16x16x32_bf16 v[38:41], v[190:193], v[230:233], v[34:37]
	v_mfma_f32_16x16x32_bf16 v[34:37], v[194:197], v[226:229], v[94:97]
	v_mfma_f32_16x16x32_bf16 v[34:37], v[198:201], v[230:233], v[34:37]
	s_setprio 0
	s_barrier
	ds_read_b128 v[202:205], v244 offset:49152
	ds_read_b128 v[206:209], v244 offset:50176
	ds_read_b128 v[210:213], v244 offset:51200
	ds_read_b128 v[214:217], v244 offset:52224
	ds_read_b128 v[218:221], v244 offset:53248
	ds_read_b128 v[222:225], v244 offset:54272
	ds_read_b128 v[226:229], v244 offset:55296
	ds_read_b128 v[230:233], v244 offset:56320
	s_mov_b32 m0, s56
	s_nop 0
	global_load_lds_dwordx4 v240, s[36:37]
	s_nop 0
	s_mov_b32 m0, s57
	s_nop 0
	global_load_lds_dwordx4 v242, s[36:37]
	s_add_u32 s36, s25, 0x180
	s_addc_u32 s37, s40, 0
	s_mov_b32 m0, s60
	s_nop 0
	global_load_lds_dwordx4 v240, s[36:37]
	s_nop 0
	s_mov_b32 m0, s61
	s_nop 0
	global_load_lds_dwordx4 v242, s[36:37]
	s_nop 0
	s_mov_b32 m0, s58
	s_nop 0
	global_load_lds_dwordx4 v0, s[8:9]
	s_nop 0
	s_mov_b32 m0, s59
	s_nop 0
	global_load_lds_dwordx4 v241, s[8:9]
	s_waitcnt vmcnt(8)
	s_waitcnt lgkmcnt(0)
	s_barrier
	s_setprio 1
	s_waitcnt lgkmcnt(7)
	v_mfma_f32_16x16x32_bf16 v[66:69], v[6:9], v[202:205], v[148:151]
	s_waitcnt lgkmcnt(6)
	v_mfma_f32_16x16x32_bf16 v[94:97], v[10:13], v[206:209], v[66:69]
	v_mfma_f32_16x16x32_bf16 v[66:69], v[14:17], v[202:205], v[152:155]
	v_mfma_f32_16x16x32_bf16 v[90:93], v[30:33], v[206:209], v[66:69]
	s_waitcnt lgkmcnt(5)
	v_mfma_f32_16x16x32_bf16 v[66:69], v[6:9], v[210:213], v[156:159]
	s_waitcnt lgkmcnt(4)
	v_mfma_f32_16x16x32_bf16 v[86:89], v[10:13], v[214:217], v[66:69]
	v_mfma_f32_16x16x32_bf16 v[66:69], v[14:17], v[210:213], v[160:163]
	v_mfma_f32_16x16x32_bf16 v[82:85], v[30:33], v[214:217], v[66:69]
	s_waitcnt lgkmcnt(3)
	v_mfma_f32_16x16x32_bf16 v[66:69], v[6:9], v[218:221], v[164:167]
	s_waitcnt lgkmcnt(1)
	v_mfma_f32_16x16x32_bf16 v[6:9], v[6:9], v[226:229], v[18:21]
	v_mfma_f32_16x16x32_bf16 v[78:81], v[10:13], v[222:225], v[66:69]
	v_mfma_f32_16x16x32_bf16 v[66:69], v[14:17], v[218:221], v[168:171]
	s_waitcnt lgkmcnt(0)
	v_mfma_f32_16x16x32_bf16 v[70:73], v[10:13], v[230:233], v[6:9]
	v_mfma_f32_16x16x32_bf16 v[6:9], v[14:17], v[226:229], v[22:25]
	v_mfma_f32_16x16x32_bf16 v[74:77], v[30:33], v[222:225], v[66:69]
	v_mfma_f32_16x16x32_bf16 v[66:69], v[30:33], v[230:233], v[6:9]
	s_setprio 0
	s_setprio 1
	v_mfma_f32_16x16x32_bf16 v[6:9], v[110:113], v[202:205], v[26:29]
	v_mfma_f32_16x16x32_bf16 v[30:33], v[190:193], v[206:209], v[6:9]
	v_mfma_f32_16x16x32_bf16 v[6:9], v[194:197], v[202:205], v[172:175]
	v_mfma_f32_16x16x32_bf16 v[26:29], v[198:201], v[206:209], v[6:9]
	v_mfma_f32_16x16x32_bf16 v[6:9], v[110:113], v[210:213], v[176:179]
	v_mfma_f32_16x16x32_bf16 v[22:25], v[190:193], v[214:217], v[6:9]
	v_mfma_f32_16x16x32_bf16 v[6:9], v[194:197], v[210:213], v[182:185]
	v_mfma_f32_16x16x32_bf16 v[18:21], v[198:201], v[214:217], v[6:9]
	v_mfma_f32_16x16x32_bf16 v[6:9], v[110:113], v[218:221], v[186:189]
	v_mfma_f32_16x16x32_bf16 v[14:17], v[190:193], v[222:225], v[6:9]
	v_mfma_f32_16x16x32_bf16 v[6:9], v[194:197], v[218:221], v[106:109]
	v_mfma_f32_16x16x32_bf16 v[2:5], v[110:113], v[226:229], v[2:5]
	v_mfma_f32_16x16x32_bf16 v[10:13], v[198:201], v[222:225], v[6:9]
	v_mfma_f32_16x16x32_bf16 v[6:9], v[190:193], v[230:233], v[2:5]
	v_mfma_f32_16x16x32_bf16 v[2:5], v[194:197], v[226:229], v[100:103]
	v_mfma_f32_16x16x32_bf16 v[2:5], v[198:201], v[230:233], v[2:5]
	s_setprio 0
	s_barrier
	s_add_u32 s25, s30, 0x200
	s_addc_u32 s66, s31, 0
	s_add_u32 s8, s34, 0x80180
	s_addc_u32 s9, s35, 0
	s_mov_b32 s67, 4
	.p2align	6

.LBB0_1154:
	s_ashr_i32 s15, s14, 31
	s_lshl_b64 s[16:17], s[14:15], 20
	s_add_u32 s16, s30, s16
	s_addc_u32 s17, s31, s17
	s_and_b64 s[18:19], s[6:7], exec
	s_cselect_b32 s15, s17, s23
	s_cselect_b32 s55, s16, s22
	s_ashr_i32 s13, s12, 31
	s_lshl_b64 s[18:19], s[12:13], 20
	s_add_u32 s18, s34, s18
	s_addc_u32 s19, s35, s19
	s_and_b64 s[24:25], s[6:7], exec
	s_cselect_b32 s13, s19, s21
	s_cselect_b32 s56, s18, s20
	s_add_u32 s24, s22, 0x180
	s_waitcnt lgkmcnt(0)
	s_addc_u32 s25, s23, 0
	s_add_u32 s26, s20, 0x180
	s_addc_u32 s27, s21, 0
	s_barrier
	s_setprio 1
	s_waitcnt lgkmcnt(7)
	v_mfma_f32_16x16x32_bf16 v[122:125], v[18:21], v[114:117], 0
	s_waitcnt lgkmcnt(6)
	v_mfma_f32_16x16x32_bf16 v[164:167], v[22:25], v[118:121], v[122:125]
	v_mfma_f32_16x16x32_bf16 v[122:125], v[26:29], v[114:117], 0
	v_mfma_f32_16x16x32_bf16 v[168:171], v[30:33], v[118:121], v[122:125]
	s_waitcnt lgkmcnt(5)
	v_mfma_f32_16x16x32_bf16 v[122:125], v[18:21], v[106:109], 0
	s_waitcnt lgkmcnt(4)
	v_mfma_f32_16x16x32_bf16 v[172:175], v[22:25], v[110:113], v[122:125]
	v_mfma_f32_16x16x32_bf16 v[122:125], v[26:29], v[106:109], 0
	v_mfma_f32_16x16x32_bf16 v[176:179], v[30:33], v[110:113], v[122:125]
	s_waitcnt lgkmcnt(3)
	v_mfma_f32_16x16x32_bf16 v[122:125], v[18:21], v[98:101], 0
	s_waitcnt lgkmcnt(1)
	v_mfma_f32_16x16x32_bf16 v[18:21], v[18:21], v[82:85], 0
	v_mfma_f32_16x16x32_bf16 v[182:185], v[22:25], v[102:105], v[122:125]
	v_mfma_f32_16x16x32_bf16 v[122:125], v[26:29], v[98:101], 0
	s_waitcnt lgkmcnt(0)
	v_mfma_f32_16x16x32_bf16 v[22:25], v[22:25], v[90:93], v[18:21]
	v_mfma_f32_16x16x32_bf16 v[18:21], v[26:29], v[82:85], 0
	v_mfma_f32_16x16x32_bf16 v[186:189], v[30:33], v[102:105], v[122:125]
	v_mfma_f32_16x16x32_bf16 v[30:33], v[30:33], v[90:93], v[18:21]
	s_setprio 0
	s_setprio 1
	v_mfma_f32_16x16x32_bf16 v[18:21], v[2:5], v[114:117], 0
	v_mfma_f32_16x16x32_bf16 v[190:193], v[6:9], v[118:121], v[18:21]
	v_mfma_f32_16x16x32_bf16 v[18:21], v[10:13], v[114:117], 0
	v_mfma_f32_16x16x32_bf16 v[194:197], v[14:17], v[118:121], v[18:21]
	v_mfma_f32_16x16x32_bf16 v[18:21], v[2:5], v[106:109], 0
	v_mfma_f32_16x16x32_bf16 v[198:201], v[6:9], v[110:113], v[18:21]
	v_mfma_f32_16x16x32_bf16 v[18:21], v[10:13], v[106:109], 0
	v_mfma_f32_16x16x32_bf16 v[202:205], v[14:17], v[110:113], v[18:21]
	v_mfma_f32_16x16x32_bf16 v[18:21], v[2:5], v[98:101], 0
	v_mfma_f32_16x16x32_bf16 v[2:5], v[2:5], v[82:85], 0
	v_mfma_f32_16x16x32_bf16 v[206:209], v[6:9], v[102:105], v[18:21]
	v_mfma_f32_16x16x32_bf16 v[18:21], v[10:13], v[98:101], 0
	v_mfma_f32_16x16x32_bf16 v[6:9], v[6:9], v[90:93], v[2:5]
	v_mfma_f32_16x16x32_bf16 v[2:5], v[10:13], v[82:85], 0
	v_mfma_f32_16x16x32_bf16 v[210:213], v[14:17], v[102:105], v[18:21]
	v_mfma_f32_16x16x32_bf16 v[214:217], v[14:17], v[90:93], v[2:5]
	s_setprio 0
	s_barrier
	v_add_u32_e32 v161, 0x18000, v159
	v_add_u32_e32 v162, 0x1c000, v159
	s_nop 1
	ds_read_b128 v[2:5], v161
	ds_read_b128 v[10:13], v161 offset:1024
	ds_read_b128 v[14:17], v161 offset:2048
	ds_read_b128 v[218:221], v161 offset:3072
	ds_read_b128 v[222:225], v162
	ds_read_b128 v[226:229], v162 offset:1024
	ds_read_b128 v[230:233], v162 offset:2048
	ds_read_b128 v[240:243], v162 offset:3072
	ds_read_b128 v[18:21], v160 offset:32768
	ds_read_b128 v[26:29], v160 offset:33792
	ds_read_b128 v[102:105], v160 offset:34816
	ds_read_b128 v[110:113], v160 offset:35840
	ds_read_b128 v[244:247], v160 offset:36864
	ds_read_b128 v[34:37], v160 offset:37888
	ds_read_b128 v[38:41], v160 offset:38912
	ds_read_b128 v[42:45], v160 offset:39936
	s_add_u32 s28, s22, 0x80100
	s_addc_u32 s29, s23, 0
	s_mov_b32 m0, s44
	s_nop 0
	global_load_lds_dwordx4 v0, s[28:29]
	s_nop 0
	s_mov_b32 m0, s45
	s_nop 0
	global_load_lds_dwordx4 v157, s[28:29]
	s_waitcnt vmcnt(8)
	s_waitcnt lgkmcnt(0)
	s_barrier
	s_setprio 1
	s_waitcnt lgkmcnt(5)
	v_mfma_f32_16x16x32_bf16 v[46:49], v[14:17], v[102:105], v[46:49]
	s_waitcnt lgkmcnt(4)
	v_mfma_f32_16x16x32_bf16 v[114:117], v[218:221], v[110:113], v[46:49]
	s_waitcnt lgkmcnt(3)
	v_mfma_f32_16x16x32_bf16 v[46:49], v[2:5], v[244:247], v[50:53]
	v_mfma_f32_16x16x32_bf16 v[82:85], v[2:5], v[18:21], v[126:129]
	s_waitcnt lgkmcnt(2)
	v_mfma_f32_16x16x32_bf16 v[106:109], v[10:13], v[34:37], v[46:49]
	v_mfma_f32_16x16x32_bf16 v[46:49], v[14:17], v[244:247], v[54:57]
	v_mfma_f32_16x16x32_bf16 v[138:141], v[10:13], v[26:29], v[82:85]
	v_mfma_f32_16x16x32_bf16 v[82:85], v[14:17], v[18:21], v[130:133]
	v_mfma_f32_16x16x32_bf16 v[98:101], v[218:221], v[34:37], v[46:49]
	s_waitcnt lgkmcnt(1)
	v_mfma_f32_16x16x32_bf16 v[46:49], v[2:5], v[38:41], v[58:61]
	v_mfma_f32_16x16x32_bf16 v[130:133], v[218:221], v[26:29], v[82:85]
	v_mfma_f32_16x16x32_bf16 v[82:85], v[2:5], v[102:105], v[134:137]
	s_waitcnt lgkmcnt(0)
	v_mfma_f32_16x16x32_bf16 v[90:93], v[10:13], v[42:45], v[46:49]
	v_mfma_f32_16x16x32_bf16 v[46:49], v[14:17], v[38:41], v[62:65]
	v_mfma_f32_16x16x32_bf16 v[122:125], v[10:13], v[110:113], v[82:85]
	v_mfma_f32_16x16x32_bf16 v[82:85], v[218:221], v[42:45], v[46:49]
	s_setprio 0
	s_setprio 1
	v_mfma_f32_16x16x32_bf16 v[46:49], v[222:225], v[18:21], v[66:69]
	v_mfma_f32_16x16x32_bf16 v[18:21], v[230:233], v[18:21], v[70:73]
	v_mfma_f32_16x16x32_bf16 v[134:137], v[240:243], v[26:29], v[18:21]
	v_mfma_f32_16x16x32_bf16 v[18:21], v[222:225], v[102:105], v[74:77]
	v_mfma_f32_16x16x32_bf16 v[126:129], v[226:229], v[110:113], v[18:21]
	v_mfma_f32_16x16x32_bf16 v[18:21], v[230:233], v[102:105], v[78:81]
	v_mfma_f32_16x16x32_bf16 v[118:121], v[240:243], v[110:113], v[18:21]
	v_mfma_f32_16x16x32_bf16 v[18:21], v[222:225], v[244:247], v[86:89]
	v_mfma_f32_16x16x32_bf16 v[110:113], v[226:229], v[34:37], v[18:21]
	v_mfma_f32_16x16x32_bf16 v[18:21], v[230:233], v[244:247], v[94:97]
	v_mfma_f32_16x16x32_bf16 v[102:105], v[240:243], v[34:37], v[18:21]
	v_mfma_f32_16x16x32_bf16 v[18:21], v[222:225], v[38:41], v[146:149]
	v_mfma_f32_16x16x32_bf16 v[94:97], v[226:229], v[42:45], v[18:21]
	v_mfma_f32_16x16x32_bf16 v[18:21], v[230:233], v[38:41], v[150:153]
	v_mfma_f32_16x16x32_bf16 v[142:145], v[226:229], v[26:29], v[46:49]
	v_mfma_f32_16x16x32_bf16 v[86:89], v[240:243], v[42:45], v[18:21]
	s_setprio 0
	s_barrier
	ds_read_b128 v[38:41], v160 offset:49152
	ds_read_b128 v[46:49], v160 offset:50176
	ds_read_b128 v[50:53], v160 offset:51200
	ds_read_b128 v[54:57], v160 offset:52224
	ds_read_b128 v[62:65], v160 offset:53248
	ds_read_b128 v[66:69], v160 offset:54272
	ds_read_b128 v[146:149], v160 offset:55296
	ds_read_b128 v[150:153], v160 offset:56320
	s_mov_b32 m0, s46
	s_nop 0
	global_load_lds_dwordx4 v156, s[26:27]
	s_nop 0
	s_mov_b32 m0, s47
	s_nop 0
	global_load_lds_dwordx4 v158, s[26:27]
	s_add_u32 s26, s20, 0x80180
	s_addc_u32 s27, s21, 0
	s_mov_b32 m0, s50
	s_nop 0
	global_load_lds_dwordx4 v156, s[26:27]
	s_nop 0
	s_mov_b32 m0, s51
	s_nop 0
	global_load_lds_dwordx4 v158, s[26:27]
	s_nop 0
	s_mov_b32 m0, s48
	s_nop 0
	global_load_lds_dwordx4 v0, s[24:25]
	s_nop 0
	s_mov_b32 m0, s49
	s_nop 0
	global_load_lds_dwordx4 v157, s[24:25]
	s_waitcnt vmcnt(8)
	s_waitcnt lgkmcnt(0)
	s_barrier
	s_setprio 1
	s_waitcnt lgkmcnt(7)
	v_mfma_f32_16x16x32_bf16 v[18:21], v[2:5], v[38:41], v[164:167]
	s_waitcnt lgkmcnt(6)
	v_mfma_f32_16x16x32_bf16 v[74:77], v[10:13], v[46:49], v[18:21]
	v_mfma_f32_16x16x32_bf16 v[18:21], v[14:17], v[38:41], v[168:171]
	v_mfma_f32_16x16x32_bf16 v[58:61], v[218:221], v[46:49], v[18:21]
	s_waitcnt lgkmcnt(5)
	v_mfma_f32_16x16x32_bf16 v[18:21], v[2:5], v[50:53], v[172:175]
	s_waitcnt lgkmcnt(4)
	v_mfma_f32_16x16x32_bf16 v[42:45], v[10:13], v[54:57], v[18:21]
	v_mfma_f32_16x16x32_bf16 v[18:21], v[14:17], v[50:53], v[176:179]
	v_mfma_f32_16x16x32_bf16 v[34:37], v[218:221], v[54:57], v[18:21]
	s_waitcnt lgkmcnt(3)
	v_mfma_f32_16x16x32_bf16 v[18:21], v[2:5], v[62:65], v[182:185]
	s_waitcnt lgkmcnt(1)
	v_mfma_f32_16x16x32_bf16 v[2:5], v[2:5], v[146:149], v[22:25]
	v_mfma_f32_16x16x32_bf16 v[26:29], v[10:13], v[66:69], v[18:21]
	v_mfma_f32_16x16x32_bf16 v[18:21], v[14:17], v[62:65], v[186:189]
	s_waitcnt lgkmcnt(0)
	v_mfma_f32_16x16x32_bf16 v[10:13], v[10:13], v[150:153], v[2:5]
	v_mfma_f32_16x16x32_bf16 v[2:5], v[14:17], v[146:149], v[30:33]
	v_mfma_f32_16x16x32_bf16 v[18:21], v[218:221], v[66:69], v[18:21]
	v_mfma_f32_16x16x32_bf16 v[2:5], v[218:221], v[150:153], v[2:5]
	s_setprio 0
	s_setprio 1
	v_mfma_f32_16x16x32_bf16 v[14:17], v[222:225], v[38:41], v[190:193]
	v_mfma_f32_16x16x32_bf16 v[78:81], v[226:229], v[46:49], v[14:17]
	v_mfma_f32_16x16x32_bf16 v[14:17], v[230:233], v[38:41], v[194:197]
	v_mfma_f32_16x16x32_bf16 v[70:73], v[240:243], v[46:49], v[14:17]
	v_mfma_f32_16x16x32_bf16 v[14:17], v[222:225], v[50:53], v[198:201]
	v_mfma_f32_16x16x32_bf16 v[46:49], v[226:229], v[54:57], v[14:17]
	v_mfma_f32_16x16x32_bf16 v[14:17], v[230:233], v[50:53], v[202:205]
	v_mfma_f32_16x16x32_bf16 v[38:41], v[240:243], v[54:57], v[14:17]
	v_mfma_f32_16x16x32_bf16 v[14:17], v[222:225], v[62:65], v[206:209]
	v_mfma_f32_16x16x32_bf16 v[30:33], v[226:229], v[66:69], v[14:17]
	v_mfma_f32_16x16x32_bf16 v[14:17], v[230:233], v[62:65], v[210:213]
	v_mfma_f32_16x16x32_bf16 v[6:9], v[222:225], v[146:149], v[6:9]
	v_mfma_f32_16x16x32_bf16 v[22:25], v[240:243], v[66:69], v[14:17]
	v_mfma_f32_16x16x32_bf16 v[14:17], v[226:229], v[150:153], v[6:9]
	v_mfma_f32_16x16x32_bf16 v[6:9], v[230:233], v[146:149], v[214:217]
	v_mfma_f32_16x16x32_bf16 v[6:9], v[240:243], v[150:153], v[6:9]
	s_setprio 0
	s_barrier
	s_add_u32 s57, s20, 0x200
	s_addc_u32 s58, s21, 0
	s_add_u32 s20, s22, 0x80180
	s_addc_u32 s21, s23, 0
	s_mov_b32 s59, 0
	.p2align	6

.LBB0_1232:
	s_add_u32 s6, s8, 0x180
	s_waitcnt lgkmcnt(0)
	s_addc_u32 s7, s9, 0
	s_add_u32 s34, s30, 0x180
	s_addc_u32 s35, s31, 0
	s_barrier
	s_setprio 1
	s_waitcnt lgkmcnt(7)
	v_mfma_f32_16x16x32_bf16 v[130:133], v[18:21], v[122:125], 0
	s_waitcnt lgkmcnt(6)
	v_mfma_f32_16x16x32_bf16 v[156:159], v[22:25], v[126:129], v[130:133]
	v_mfma_f32_16x16x32_bf16 v[130:133], v[26:29], v[122:125], 0
	v_mfma_f32_16x16x32_bf16 v[160:163], v[30:33], v[126:129], v[130:133]
	s_waitcnt lgkmcnt(5)
	v_mfma_f32_16x16x32_bf16 v[130:133], v[18:21], v[114:117], 0
	s_waitcnt lgkmcnt(4)
	v_mfma_f32_16x16x32_bf16 v[164:167], v[22:25], v[118:121], v[130:133]
	v_mfma_f32_16x16x32_bf16 v[130:133], v[26:29], v[114:117], 0
	v_mfma_f32_16x16x32_bf16 v[168:171], v[30:33], v[118:121], v[130:133]
	s_waitcnt lgkmcnt(3)
	v_mfma_f32_16x16x32_bf16 v[130:133], v[18:21], v[106:109], 0
	s_waitcnt lgkmcnt(1)
	v_mfma_f32_16x16x32_bf16 v[18:21], v[18:21], v[98:101], 0
	v_mfma_f32_16x16x32_bf16 v[172:175], v[22:25], v[110:113], v[130:133]
	s_waitcnt lgkmcnt(0)
	v_mfma_f32_16x16x32_bf16 v[18:21], v[22:25], v[102:105], v[18:21]
	v_mfma_f32_16x16x32_bf16 v[22:25], v[26:29], v[98:101], 0
	v_mfma_f32_16x16x32_bf16 v[130:133], v[26:29], v[106:109], 0
	v_mfma_f32_16x16x32_bf16 v[22:25], v[30:33], v[102:105], v[22:25]
	v_mfma_f32_16x16x32_bf16 v[176:179], v[30:33], v[110:113], v[130:133]
	s_setprio 0
	s_setprio 1
	v_mfma_f32_16x16x32_bf16 v[30:33], v[10:13], v[122:125], 0
	v_mfma_f32_16x16x32_bf16 v[182:185], v[14:17], v[126:129], v[30:33]
	v_mfma_f32_16x16x32_bf16 v[30:33], v[2:5], v[114:117], 0
	v_mfma_f32_16x16x32_bf16 v[186:189], v[6:9], v[118:121], v[30:33]
	v_mfma_f32_16x16x32_bf16 v[30:33], v[10:13], v[114:117], 0
	v_mfma_f32_16x16x32_bf16 v[26:29], v[2:5], v[122:125], 0
	v_mfma_f32_16x16x32_bf16 v[190:193], v[14:17], v[118:121], v[30:33]
	v_mfma_f32_16x16x32_bf16 v[30:33], v[2:5], v[106:109], 0
	v_mfma_f32_16x16x32_bf16 v[2:5], v[2:5], v[98:101], 0
	v_mfma_f32_16x16x32_bf16 v[26:29], v[6:9], v[126:129], v[26:29]
	v_mfma_f32_16x16x32_bf16 v[194:197], v[6:9], v[110:113], v[30:33]
	v_mfma_f32_16x16x32_bf16 v[30:33], v[10:13], v[106:109], 0
	v_mfma_f32_16x16x32_bf16 v[2:5], v[6:9], v[102:105], v[2:5]
	v_mfma_f32_16x16x32_bf16 v[6:9], v[10:13], v[98:101], 0
	v_mfma_f32_16x16x32_bf16 v[106:109], v[14:17], v[110:113], v[30:33]
	v_mfma_f32_16x16x32_bf16 v[100:103], v[14:17], v[102:105], v[6:9]
	s_setprio 0
	s_barrier
	v_add_u32_e32 v98, 0x18000, v227
	v_add_u32_e32 v99, 0x1c000, v227
	s_nop 1
	ds_read_b128 v[6:9], v98
	ds_read_b128 v[10:13], v98 offset:1024
	ds_read_b128 v[14:17], v98 offset:2048
	ds_read_b128 v[30:33], v98 offset:3072
	ds_read_b128 v[110:113], v99
	ds_read_b128 v[198:201], v99 offset:1024
	ds_read_b128 v[202:205], v99 offset:2048
	ds_read_b128 v[206:209], v99 offset:3072
	ds_read_b128 v[114:117], v228 offset:32768
	ds_read_b128 v[118:121], v228 offset:33792
	ds_read_b128 v[210:213], v228 offset:34816
	ds_read_b128 v[214:217], v228 offset:35840
	ds_read_b128 v[218:221], v228 offset:36864
	ds_read_b128 v[230:233], v228 offset:37888
	ds_read_b128 v[240:243], v228 offset:38912
	ds_read_b128 v[244:247], v228 offset:39936
	s_add_u32 s36, s8, 0x160100
	s_addc_u32 s37, s9, 0
	s_mov_b32 m0, s48
	s_nop 0
	global_load_lds_dwordx4 v0, s[36:37]
	s_nop 0
	s_mov_b32 m0, s49
	s_nop 0
	global_load_lds_dwordx4 v225, s[36:37]
	s_waitcnt vmcnt(8)
	s_waitcnt lgkmcnt(0)
	s_barrier
	s_setprio 1
	s_waitcnt lgkmcnt(7)
	v_mfma_f32_16x16x32_bf16 v[34:37], v[6:9], v[114:117], v[34:37]
	s_waitcnt lgkmcnt(6)
	v_mfma_f32_16x16x32_bf16 v[150:153], v[10:13], v[118:121], v[34:37]
	v_mfma_f32_16x16x32_bf16 v[34:37], v[14:17], v[114:117], v[38:41]
	v_mfma_f32_16x16x32_bf16 v[146:149], v[30:33], v[118:121], v[34:37]
	s_waitcnt lgkmcnt(5)
	v_mfma_f32_16x16x32_bf16 v[34:37], v[6:9], v[210:213], v[42:45]
	s_waitcnt lgkmcnt(4)
	v_mfma_f32_16x16x32_bf16 v[142:145], v[10:13], v[214:217], v[34:37]
	v_mfma_f32_16x16x32_bf16 v[34:37], v[14:17], v[210:213], v[46:49]
	v_mfma_f32_16x16x32_bf16 v[138:141], v[30:33], v[214:217], v[34:37]
	s_waitcnt lgkmcnt(3)
	v_mfma_f32_16x16x32_bf16 v[34:37], v[6:9], v[218:221], v[50:53]
	s_waitcnt lgkmcnt(2)
	v_mfma_f32_16x16x32_bf16 v[134:137], v[10:13], v[230:233], v[34:37]
	v_mfma_f32_16x16x32_bf16 v[34:37], v[14:17], v[218:221], v[54:57]
	v_mfma_f32_16x16x32_bf16 v[130:133], v[30:33], v[230:233], v[34:37]
	s_waitcnt lgkmcnt(1)
	v_mfma_f32_16x16x32_bf16 v[34:37], v[6:9], v[240:243], v[58:61]
	s_waitcnt lgkmcnt(0)
	v_mfma_f32_16x16x32_bf16 v[126:129], v[10:13], v[244:247], v[34:37]
	v_mfma_f32_16x16x32_bf16 v[34:37], v[14:17], v[240:243], v[62:65]
	v_mfma_f32_16x16x32_bf16 v[122:125], v[30:33], v[244:247], v[34:37]
	s_setprio 0
	s_setprio 1
	v_mfma_f32_16x16x32_bf16 v[34:37], v[110:113], v[114:117], v[66:69]
	v_mfma_f32_16x16x32_bf16 v[62:65], v[198:201], v[118:121], v[34:37]
	v_mfma_f32_16x16x32_bf16 v[34:37], v[202:205], v[114:117], v[70:73]
	v_mfma_f32_16x16x32_bf16 v[58:61], v[206:209], v[118:121], v[34:37]
	v_mfma_f32_16x16x32_bf16 v[34:37], v[110:113], v[210:213], v[74:77]
	v_mfma_f32_16x16x32_bf16 v[54:57], v[198:201], v[214:217], v[34:37]
	v_mfma_f32_16x16x32_bf16 v[34:37], v[202:205], v[210:213], v[78:81]
	v_mfma_f32_16x16x32_bf16 v[50:53], v[206:209], v[214:217], v[34:37]
	v_mfma_f32_16x16x32_bf16 v[34:37], v[110:113], v[218:221], v[82:85]
	v_mfma_f32_16x16x32_bf16 v[46:49], v[198:201], v[230:233], v[34:37]
	v_mfma_f32_16x16x32_bf16 v[34:37], v[202:205], v[218:221], v[86:89]
	v_mfma_f32_16x16x32_bf16 v[42:45], v[206:209], v[230:233], v[34:37]
	v_mfma_f32_16x16x32_bf16 v[34:37], v[110:113], v[240:243], v[90:93]
	v_mfma_f32_16x16x32_bf16 v[38:41], v[198:201], v[244:247], v[34:37]
	v_mfma_f32_16x16x32_bf16 v[34:37], v[202:205], v[240:243], v[94:97]
	v_mfma_f32_16x16x32_bf16 v[34:37], v[206:209], v[244:247], v[34:37]
	s_setprio 0
	s_barrier
	ds_read_b128 v[90:93], v228 offset:49152
	ds_read_b128 v[94:97], v228 offset:50176
	ds_read_b128 v[210:213], v228 offset:51200
	ds_read_b128 v[214:217], v228 offset:52224
	ds_read_b128 v[218:221], v228 offset:53248
	ds_read_b128 v[230:233], v228 offset:54272
	ds_read_b128 v[240:243], v228 offset:55296
	ds_read_b128 v[244:247], v228 offset:56320
	s_mov_b32 m0, s50
	s_nop 0
	global_load_lds_dwordx4 v224, s[34:35]
	s_nop 0
	s_mov_b32 m0, s51
	s_nop 0
	global_load_lds_dwordx4 v226, s[34:35]
	s_add_u32 s34, s30, 0x160180
	s_addc_u32 s35, s31, 0
	s_mov_b32 m0, s54
	s_nop 0
	global_load_lds_dwordx4 v224, s[34:35]
	s_nop 0
	s_mov_b32 m0, s55
	s_nop 0
	global_load_lds_dwordx4 v226, s[34:35]
	s_nop 0
	s_mov_b32 m0, s52
	s_nop 0
	global_load_lds_dwordx4 v0, s[6:7]
	s_nop 0
	s_mov_b32 m0, s53
	s_nop 0
	global_load_lds_dwordx4 v225, s[6:7]
	s_waitcnt vmcnt(8)
	s_waitcnt lgkmcnt(0)
	s_barrier
	s_setprio 1
	s_waitcnt lgkmcnt(7)
	v_mfma_f32_16x16x32_bf16 v[66:69], v[6:9], v[90:93], v[156:159]
	s_waitcnt lgkmcnt(6)
	v_mfma_f32_16x16x32_bf16 v[118:121], v[10:13], v[94:97], v[66:69]
	v_mfma_f32_16x16x32_bf16 v[66:69], v[14:17], v[90:93], v[160:163]
	v_mfma_f32_16x16x32_bf16 v[114:117], v[30:33], v[94:97], v[66:69]
	s_waitcnt lgkmcnt(5)
	v_mfma_f32_16x16x32_bf16 v[66:69], v[6:9], v[210:213], v[164:167]
	s_waitcnt lgkmcnt(4)
	v_mfma_f32_16x16x32_bf16 v[86:89], v[10:13], v[214:217], v[66:69]
	v_mfma_f32_16x16x32_bf16 v[66:69], v[14:17], v[210:213], v[168:171]
	v_mfma_f32_16x16x32_bf16 v[82:85], v[30:33], v[214:217], v[66:69]
	s_waitcnt lgkmcnt(3)
	v_mfma_f32_16x16x32_bf16 v[66:69], v[6:9], v[218:221], v[172:175]
	s_waitcnt lgkmcnt(1)
	v_mfma_f32_16x16x32_bf16 v[6:9], v[6:9], v[240:243], v[18:21]
	v_mfma_f32_16x16x32_bf16 v[78:81], v[10:13], v[230:233], v[66:69]
	v_mfma_f32_16x16x32_bf16 v[66:69], v[14:17], v[218:221], v[176:179]
	s_waitcnt lgkmcnt(0)
	v_mfma_f32_16x16x32_bf16 v[70:73], v[10:13], v[244:247], v[6:9]
	v_mfma_f32_16x16x32_bf16 v[6:9], v[14:17], v[240:243], v[22:25]
	v_mfma_f32_16x16x32_bf16 v[74:77], v[30:33], v[230:233], v[66:69]
	v_mfma_f32_16x16x32_bf16 v[66:69], v[30:33], v[244:247], v[6:9]
	s_setprio 0
	s_setprio 1
	v_mfma_f32_16x16x32_bf16 v[6:9], v[110:113], v[90:93], v[26:29]
	v_mfma_f32_16x16x32_bf16 v[30:33], v[198:201], v[94:97], v[6:9]
	v_mfma_f32_16x16x32_bf16 v[6:9], v[202:205], v[90:93], v[182:185]
	v_mfma_f32_16x16x32_bf16 v[26:29], v[206:209], v[94:97], v[6:9]
	v_mfma_f32_16x16x32_bf16 v[6:9], v[110:113], v[210:213], v[186:189]
	v_mfma_f32_16x16x32_bf16 v[22:25], v[198:201], v[214:217], v[6:9]
	v_mfma_f32_16x16x32_bf16 v[6:9], v[202:205], v[210:213], v[190:193]
	v_mfma_f32_16x16x32_bf16 v[18:21], v[206:209], v[214:217], v[6:9]
	v_mfma_f32_16x16x32_bf16 v[6:9], v[110:113], v[218:221], v[194:197]
	v_mfma_f32_16x16x32_bf16 v[14:17], v[198:201], v[230:233], v[6:9]
	v_mfma_f32_16x16x32_bf16 v[6:9], v[202:205], v[218:221], v[106:109]
	v_mfma_f32_16x16x32_bf16 v[2:5], v[110:113], v[240:243], v[2:5]
	v_mfma_f32_16x16x32_bf16 v[10:13], v[206:209], v[230:233], v[6:9]
	v_mfma_f32_16x16x32_bf16 v[6:9], v[198:201], v[244:247], v[2:5]
	v_mfma_f32_16x16x32_bf16 v[2:5], v[202:205], v[240:243], v[100:103]
	v_mfma_f32_16x16x32_bf16 v[2:5], v[206:209], v[244:247], v[2:5]
	s_setprio 0
	s_barrier
	s_add_u32 s61, s30, 0x200
	s_addc_u32 s62, s31, 0
	s_add_u32 s6, s8, 0x160180
	s_addc_u32 s7, s9, 0
	s_mov_b32 s63, 0
	.p2align	6
